# adds: fox_cumsum eight per-head wave scans interleaved (independent chains issued together)
# speedup vs baseline: 1.0057x; 1.0057x over previous
; __device__ __forceinline__ float wave_scan_incl(float v, int lane) {
; #pragma unroll
;     for (int o = 1; o < 64; o <<= 1) { float t = __shfl_up(v, o); if (lane >= o) v += t; }
;     return v;
; __device__ __forceinline__ void fox_cumsum(const Params& P, LAS unsigned char* lds, int layer, int tid, int lane, int wave) {
;     ...
;         if (wave == 0) {
; #pragma unroll
;             for (int h = 0; h < 8; ++h) { const float c = wave_scan_incl(hv[h], lane); CL[(krow0 + lane) * 8 + h] = c; const float cm = wave_min(c);
;                 if (lane == 63) { BT[(krow0 >> 6) * 8 + h] = c; CM[(krow0 >> 6) * 8 + h] = cm; } }
.LBB0_509:
	s_or_b64 exec, exec, s[60:61]
	s_and_b64 vcc, exec, s[56:57]
	s_cbranch_vccnz .LBB0_527
	s_lshr_b64 s[56:57], s[22:23], 3
	s_and_b32 s60, s56, -8
	s_mov_b32 s61, s57
	ds_bpermute_b32 v24, v50, v6
	ds_bpermute_b32 v25, v50, v7
	ds_bpermute_b32 v26, v50, v8
	ds_bpermute_b32 v27, v50, v9
	ds_bpermute_b32 v28, v50, v2
	ds_bpermute_b32 v29, v50, v3
	ds_bpermute_b32 v30, v50, v4
	ds_bpermute_b32 v31, v50, v5
	s_waitcnt lgkmcnt(7)
	v_add_f32_e32 v24, v6, v24
	v_cndmask_b32_e64 v16, v24, v6, s[42:43]
	s_waitcnt lgkmcnt(6)
	v_add_f32_e32 v25, v7, v25
	v_cndmask_b32_e64 v17, v25, v7, s[42:43]
	s_waitcnt lgkmcnt(5)
	v_add_f32_e32 v26, v8, v26
	v_cndmask_b32_e64 v18, v26, v8, s[42:43]
	s_waitcnt lgkmcnt(4)
	v_add_f32_e32 v27, v9, v27
	v_cndmask_b32_e64 v19, v27, v9, s[42:43]
	s_waitcnt lgkmcnt(3)
	v_add_f32_e32 v28, v2, v28
	v_cndmask_b32_e64 v20, v28, v2, s[42:43]
	s_waitcnt lgkmcnt(2)
	v_add_f32_e32 v29, v3, v29
	v_cndmask_b32_e64 v21, v29, v3, s[42:43]
	s_waitcnt lgkmcnt(1)
	v_add_f32_e32 v30, v4, v30
	v_cndmask_b32_e64 v22, v30, v4, s[42:43]
	s_waitcnt lgkmcnt(0)
	v_add_f32_e32 v31, v5, v31
	v_cndmask_b32_e64 v23, v31, v5, s[42:43]
	ds_bpermute_b32 v24, v51, v16
	ds_bpermute_b32 v25, v51, v17
	ds_bpermute_b32 v26, v51, v18
	ds_bpermute_b32 v27, v51, v19
	ds_bpermute_b32 v28, v51, v20
	ds_bpermute_b32 v29, v51, v21
	ds_bpermute_b32 v30, v51, v22
	ds_bpermute_b32 v31, v51, v23
	s_waitcnt lgkmcnt(7)
	v_add_f32_e32 v24, v16, v24
	v_cndmask_b32_e64 v16, v24, v16, s[44:45]
	s_waitcnt lgkmcnt(6)
	v_add_f32_e32 v25, v17, v25
	v_cndmask_b32_e64 v17, v25, v17, s[44:45]
	s_waitcnt lgkmcnt(5)
	v_add_f32_e32 v26, v18, v26
	v_cndmask_b32_e64 v18, v26, v18, s[44:45]
	s_waitcnt lgkmcnt(4)
	v_add_f32_e32 v27, v19, v27
	v_cndmask_b32_e64 v19, v27, v19, s[44:45]
	s_waitcnt lgkmcnt(3)
	v_add_f32_e32 v28, v20, v28
	v_cndmask_b32_e64 v20, v28, v20, s[44:45]
	s_waitcnt lgkmcnt(2)
	v_add_f32_e32 v29, v21, v29
	v_cndmask_b32_e64 v21, v29, v21, s[44:45]
	s_waitcnt lgkmcnt(1)
	v_add_f32_e32 v30, v22, v30
	v_cndmask_b32_e64 v22, v30, v22, s[44:45]
	s_waitcnt lgkmcnt(0)
	v_add_f32_e32 v31, v23, v31
	v_cndmask_b32_e64 v23, v31, v23, s[44:45]
	ds_bpermute_b32 v24, v52, v16
	ds_bpermute_b32 v25, v52, v17
	ds_bpermute_b32 v26, v52, v18
	ds_bpermute_b32 v27, v52, v19
	ds_bpermute_b32 v28, v52, v20
	ds_bpermute_b32 v29, v52, v21
	ds_bpermute_b32 v30, v52, v22
	ds_bpermute_b32 v31, v52, v23
	s_waitcnt lgkmcnt(7)
	v_add_f32_e32 v24, v16, v24
	v_cndmask_b32_e64 v16, v24, v16, s[46:47]
	s_waitcnt lgkmcnt(6)
	v_add_f32_e32 v25, v17, v25
	v_cndmask_b32_e64 v17, v25, v17, s[46:47]
	s_waitcnt lgkmcnt(5)
	v_add_f32_e32 v26, v18, v26
	v_cndmask_b32_e64 v18, v26, v18, s[46:47]
	s_waitcnt lgkmcnt(4)
	v_add_f32_e32 v27, v19, v27
	v_cndmask_b32_e64 v19, v27, v19, s[46:47]
	s_waitcnt lgkmcnt(3)
	v_add_f32_e32 v28, v20, v28
	v_cndmask_b32_e64 v20, v28, v20, s[46:47]
	s_waitcnt lgkmcnt(2)
	v_add_f32_e32 v29, v21, v29
	v_cndmask_b32_e64 v21, v29, v21, s[46:47]
	s_waitcnt lgkmcnt(1)
	v_add_f32_e32 v30, v22, v30
	v_cndmask_b32_e64 v22, v30, v22, s[46:47]
	s_waitcnt lgkmcnt(0)
	v_add_f32_e32 v31, v23, v31
	v_cndmask_b32_e64 v23, v31, v23, s[46:47]
	ds_bpermute_b32 v24, v53, v16
	ds_bpermute_b32 v25, v53, v17
	ds_bpermute_b32 v26, v53, v18
	ds_bpermute_b32 v27, v53, v19
	ds_bpermute_b32 v28, v53, v20
	ds_bpermute_b32 v29, v53, v21
	ds_bpermute_b32 v30, v53, v22
	ds_bpermute_b32 v31, v53, v23
	s_waitcnt lgkmcnt(7)
	v_add_f32_e32 v24, v16, v24
	v_cndmask_b32_e64 v16, v24, v16, s[48:49]
	s_waitcnt lgkmcnt(6)
	v_add_f32_e32 v25, v17, v25
	v_cndmask_b32_e64 v17, v25, v17, s[48:49]
	s_waitcnt lgkmcnt(5)
	v_add_f32_e32 v26, v18, v26
	v_cndmask_b32_e64 v18, v26, v18, s[48:49]
	s_waitcnt lgkmcnt(4)
	v_add_f32_e32 v27, v19, v27
	v_cndmask_b32_e64 v19, v27, v19, s[48:49]
	s_waitcnt lgkmcnt(3)
	v_add_f32_e32 v28, v20, v28
	v_cndmask_b32_e64 v20, v28, v20, s[48:49]
	s_waitcnt lgkmcnt(2)
	v_add_f32_e32 v29, v21, v29
	v_cndmask_b32_e64 v21, v29, v21, s[48:49]
	s_waitcnt lgkmcnt(1)
	v_add_f32_e32 v30, v22, v30
	v_cndmask_b32_e64 v22, v30, v22, s[48:49]
	s_waitcnt lgkmcnt(0)
	v_add_f32_e32 v31, v23, v31
	v_cndmask_b32_e64 v23, v31, v23, s[48:49]
	ds_bpermute_b32 v24, v54, v16
	ds_bpermute_b32 v25, v54, v17
	ds_bpermute_b32 v26, v54, v18
	ds_bpermute_b32 v27, v54, v19
	ds_bpermute_b32 v28, v54, v20
	ds_bpermute_b32 v29, v54, v21
	ds_bpermute_b32 v30, v54, v22
	ds_bpermute_b32 v31, v54, v23
	s_waitcnt lgkmcnt(7)
	v_add_f32_e32 v24, v16, v24
	v_cndmask_b32_e64 v16, v24, v16, s[50:51]
	s_waitcnt lgkmcnt(6)
	v_add_f32_e32 v25, v17, v25
	v_cndmask_b32_e64 v17, v25, v17, s[50:51]
	s_waitcnt lgkmcnt(5)
	v_add_f32_e32 v26, v18, v26
	v_cndmask_b32_e64 v18, v26, v18, s[50:51]
	s_waitcnt lgkmcnt(4)
	v_add_f32_e32 v27, v19, v27
	v_cndmask_b32_e64 v19, v27, v19, s[50:51]
	s_waitcnt lgkmcnt(3)
	v_add_f32_e32 v28, v20, v28
	v_cndmask_b32_e64 v20, v28, v20, s[50:51]
	s_waitcnt lgkmcnt(2)
	v_add_f32_e32 v29, v21, v29
	v_cndmask_b32_e64 v21, v29, v21, s[50:51]
	s_waitcnt lgkmcnt(1)
	v_add_f32_e32 v30, v22, v30
	v_cndmask_b32_e64 v22, v30, v22, s[50:51]
	s_waitcnt lgkmcnt(0)
	v_add_f32_e32 v31, v23, v31
	v_cndmask_b32_e64 v23, v31, v23, s[50:51]
	ds_bpermute_b32 v24, v55, v16
	ds_bpermute_b32 v25, v55, v17
	ds_bpermute_b32 v26, v55, v18
	ds_bpermute_b32 v27, v55, v19
	ds_bpermute_b32 v28, v55, v20
	ds_bpermute_b32 v29, v55, v21
	ds_bpermute_b32 v30, v55, v22
	ds_bpermute_b32 v31, v55, v23
	s_waitcnt lgkmcnt(7)
	v_add_f32_e32 v24, v16, v24
	v_cndmask_b32_e64 v16, v24, v16, s[52:53]
	s_waitcnt lgkmcnt(6)
	v_add_f32_e32 v25, v17, v25
	v_cndmask_b32_e64 v17, v25, v17, s[52:53]
	s_waitcnt lgkmcnt(5)
; __device__ __forceinline__ float wave_min(float v) {
; #pragma unroll
;     for (int o = 1; o < 64; o <<= 1) v = fminf(v, __shfl_xor(v, o));
;     return v;
; __device__ __forceinline__ void fox_cumsum(const Params& P, LAS unsigned char* lds, int layer, int tid, int lane, int wave) {
;     ...
;         if (wave == 0) {
; #pragma unroll
;             for (int h = 0; h < 8; ++h) { const float c = wave_scan_incl(hv[h], lane); CL[(krow0 + lane) * 8 + h] = c; const float cm = wave_min(c);
;                 if (lane == 63) { BT[(krow0 >> 6) * 8 + h] = c; CM[(krow0 >> 6) * 8 + h] = cm; } }
	v_add_f32_e32 v26, v18, v26
	v_cndmask_b32_e64 v18, v26, v18, s[52:53]
	s_waitcnt lgkmcnt(4)
	v_add_f32_e32 v27, v19, v27
	v_cndmask_b32_e64 v19, v27, v19, s[52:53]
	s_waitcnt lgkmcnt(3)
	v_add_f32_e32 v28, v20, v28
	v_cndmask_b32_e64 v20, v28, v20, s[52:53]
	s_waitcnt lgkmcnt(2)
	v_add_f32_e32 v29, v21, v29
	v_cndmask_b32_e64 v21, v29, v21, s[52:53]
	s_waitcnt lgkmcnt(1)
	v_add_f32_e32 v30, v22, v30
	v_cndmask_b32_e64 v22, v30, v22, s[52:53]
	s_waitcnt lgkmcnt(0)
	v_add_f32_e32 v31, v23, v31
	v_cndmask_b32_e64 v23, v31, v23, s[52:53]
	v_lshl_add_u64 v[10:11], s[22:23], 0, v[42:43]
	v_lshlrev_b64 v[10:11], 5, v[10:11]
	v_lshl_add_u64 v[10:11], s[10:11], 0, v[10:11]
	global_store_dword v[10:11], v16, off
	global_store_dword v[10:11], v17, off offset:4
	global_store_dword v[10:11], v18, off offset:8
	global_store_dword v[10:11], v19, off offset:12
	global_store_dword v[10:11], v20, off offset:16
	global_store_dword v[10:11], v21, off offset:20
	global_store_dword v[10:11], v22, off offset:24
	global_store_dword v[10:11], v23, off offset:28
	ds_bpermute_b32 v80, v0, v16
	ds_bpermute_b32 v81, v0, v17
	ds_bpermute_b32 v82, v0, v18
	ds_bpermute_b32 v83, v0, v19
	ds_bpermute_b32 v84, v0, v20
	ds_bpermute_b32 v85, v0, v21
	ds_bpermute_b32 v86, v0, v22
	ds_bpermute_b32 v87, v0, v23
	v_max_f32_e32 v72, v16, v16
	s_waitcnt lgkmcnt(7)
	v_max_f32_e32 v80, v80, v80
	v_min_f32_e32 v72, v72, v80
	v_max_f32_e32 v73, v17, v17
	s_waitcnt lgkmcnt(6)
	v_max_f32_e32 v81, v81, v81
	v_min_f32_e32 v73, v73, v81
	v_max_f32_e32 v74, v18, v18
	s_waitcnt lgkmcnt(5)
	v_max_f32_e32 v82, v82, v82
	v_min_f32_e32 v74, v74, v82
	v_max_f32_e32 v75, v19, v19
	s_waitcnt lgkmcnt(4)
	v_max_f32_e32 v83, v83, v83
	v_min_f32_e32 v75, v75, v83
	v_max_f32_e32 v76, v20, v20
	s_waitcnt lgkmcnt(3)
	v_max_f32_e32 v84, v84, v84
	v_min_f32_e32 v76, v76, v84
	v_max_f32_e32 v77, v21, v21
	s_waitcnt lgkmcnt(2)
	v_max_f32_e32 v85, v85, v85
	v_min_f32_e32 v77, v77, v85
	v_max_f32_e32 v78, v22, v22
	s_waitcnt lgkmcnt(1)
	v_max_f32_e32 v86, v86, v86
	v_min_f32_e32 v78, v78, v86
	v_max_f32_e32 v79, v23, v23
	s_waitcnt lgkmcnt(0)
	v_max_f32_e32 v87, v87, v87
	v_min_f32_e32 v79, v79, v87
	ds_bpermute_b32 v80, v48, v72
	ds_bpermute_b32 v81, v48, v73
	ds_bpermute_b32 v82, v48, v74
	ds_bpermute_b32 v83, v48, v75
	ds_bpermute_b32 v84, v48, v76
	ds_bpermute_b32 v85, v48, v77
	ds_bpermute_b32 v86, v48, v78
	ds_bpermute_b32 v87, v48, v79
	s_waitcnt lgkmcnt(7)
	v_max_f32_e32 v80, v80, v80
	v_min_f32_e32 v72, v72, v80
	s_waitcnt lgkmcnt(6)
	v_max_f32_e32 v81, v81, v81
	v_min_f32_e32 v73, v73, v81
	s_waitcnt lgkmcnt(5)
	v_max_f32_e32 v82, v82, v82
	v_min_f32_e32 v74, v74, v82
	s_waitcnt lgkmcnt(4)
	v_max_f32_e32 v83, v83, v83
	v_min_f32_e32 v75, v75, v83
	s_waitcnt lgkmcnt(3)
	v_max_f32_e32 v84, v84, v84
	v_min_f32_e32 v76, v76, v84
	s_waitcnt lgkmcnt(2)
	v_max_f32_e32 v85, v85, v85
	v_min_f32_e32 v77, v77, v85
	s_waitcnt lgkmcnt(1)
	v_max_f32_e32 v86, v86, v86
	v_min_f32_e32 v78, v78, v86
	s_waitcnt lgkmcnt(0)
	v_max_f32_e32 v87, v87, v87
	v_min_f32_e32 v79, v79, v87
	ds_bpermute_b32 v80, v49, v72
	ds_bpermute_b32 v81, v49, v73
	ds_bpermute_b32 v82, v49, v74
	ds_bpermute_b32 v83, v49, v75
	ds_bpermute_b32 v84, v49, v76
	ds_bpermute_b32 v85, v49, v77
	ds_bpermute_b32 v86, v49, v78
	ds_bpermute_b32 v87, v49, v79
	s_waitcnt lgkmcnt(7)
	v_max_f32_e32 v80, v80, v80
	v_min_f32_e32 v72, v72, v80
	s_waitcnt lgkmcnt(6)
	v_max_f32_e32 v81, v81, v81
	v_min_f32_e32 v73, v73, v81
	s_waitcnt lgkmcnt(5)
	v_max_f32_e32 v82, v82, v82
	v_min_f32_e32 v74, v74, v82
	s_waitcnt lgkmcnt(4)
	v_max_f32_e32 v83, v83, v83
	v_min_f32_e32 v75, v75, v83
	s_waitcnt lgkmcnt(3)
	v_max_f32_e32 v84, v84, v84
	v_min_f32_e32 v76, v76, v84
	s_waitcnt lgkmcnt(2)
	v_max_f32_e32 v85, v85, v85
	v_min_f32_e32 v77, v77, v85
	s_waitcnt lgkmcnt(1)
	v_max_f32_e32 v86, v86, v86
	v_min_f32_e32 v78, v78, v86
	s_waitcnt lgkmcnt(0)
	v_max_f32_e32 v87, v87, v87
	v_min_f32_e32 v79, v79, v87
	ds_bpermute_b32 v80, v56, v72
	ds_bpermute_b32 v81, v56, v73
	ds_bpermute_b32 v82, v56, v74
	ds_bpermute_b32 v83, v56, v75
	ds_bpermute_b32 v84, v56, v76
	ds_bpermute_b32 v85, v56, v77
	ds_bpermute_b32 v86, v56, v78
	ds_bpermute_b32 v87, v56, v79
	s_waitcnt lgkmcnt(7)
	v_max_f32_e32 v80, v80, v80
	v_min_f32_e32 v72, v72, v80
	s_waitcnt lgkmcnt(6)
	v_max_f32_e32 v81, v81, v81
	v_min_f32_e32 v73, v73, v81
	s_waitcnt lgkmcnt(5)
	v_max_f32_e32 v82, v82, v82
	v_min_f32_e32 v74, v74, v82
	s_waitcnt lgkmcnt(4)
	v_max_f32_e32 v83, v83, v83
	v_min_f32_e32 v75, v75, v83
	s_waitcnt lgkmcnt(3)
	v_max_f32_e32 v84, v84, v84
	v_min_f32_e32 v76, v76, v84
	s_waitcnt lgkmcnt(2)
	v_max_f32_e32 v85, v85, v85
	v_min_f32_e32 v77, v77, v85
	s_waitcnt lgkmcnt(1)
	v_max_f32_e32 v86, v86, v86
	v_min_f32_e32 v78, v78, v86
	s_waitcnt lgkmcnt(0)
	v_max_f32_e32 v87, v87, v87
	v_min_f32_e32 v79, v79, v87
	ds_bpermute_b32 v80, v57, v72
	ds_bpermute_b32 v81, v57, v73
	ds_bpermute_b32 v82, v57, v74
	ds_bpermute_b32 v83, v57, v75
	ds_bpermute_b32 v84, v57, v76
	ds_bpermute_b32 v85, v57, v77
	ds_bpermute_b32 v86, v57, v78
	ds_bpermute_b32 v87, v57, v79
	s_waitcnt lgkmcnt(7)
	v_max_f32_e32 v80, v80, v80
	v_min_f32_e32 v72, v72, v80
	s_waitcnt lgkmcnt(6)
	v_max_f32_e32 v81, v81, v81
	v_min_f32_e32 v73, v73, v81
	s_waitcnt lgkmcnt(5)
	v_max_f32_e32 v82, v82, v82
	v_min_f32_e32 v74, v74, v82
	s_waitcnt lgkmcnt(4)
	v_max_f32_e32 v83, v83, v83
	v_min_f32_e32 v75, v75, v83
	s_waitcnt lgkmcnt(3)
	v_max_f32_e32 v84, v84, v84
	v_min_f32_e32 v76, v76, v84
	s_waitcnt lgkmcnt(2)
	v_max_f32_e32 v85, v85, v85
	v_min_f32_e32 v77, v77, v85
	s_waitcnt lgkmcnt(1)
	v_max_f32_e32 v86, v86, v86
	v_min_f32_e32 v78, v78, v86
	s_waitcnt lgkmcnt(0)
	v_max_f32_e32 v87, v87, v87
	v_min_f32_e32 v79, v79, v87
	ds_bpermute_b32 v80, v58, v72
	ds_bpermute_b32 v81, v58, v73
	ds_bpermute_b32 v82, v58, v74
	ds_bpermute_b32 v83, v58, v75
	ds_bpermute_b32 v84, v58, v76
	ds_bpermute_b32 v85, v58, v77
	ds_bpermute_b32 v86, v58, v78
	ds_bpermute_b32 v87, v58, v79
	v_max_f32_e32 v72, v72, v72
	s_waitcnt lgkmcnt(7)
	v_max_f32_e32 v80, v80, v80
	v_min_f32_e32 v72, v72, v80
	v_max_f32_e32 v73, v73, v73
	s_waitcnt lgkmcnt(6)
	v_max_f32_e32 v81, v81, v81
	v_min_f32_e32 v73, v73, v81
	v_max_f32_e32 v74, v74, v74
	s_waitcnt lgkmcnt(5)
	v_max_f32_e32 v82, v82, v82
	v_min_f32_e32 v74, v74, v82
	v_max_f32_e32 v75, v75, v75
	s_waitcnt lgkmcnt(4)
	v_max_f32_e32 v83, v83, v83
	v_min_f32_e32 v75, v75, v83
	v_max_f32_e32 v76, v76, v76
	s_waitcnt lgkmcnt(3)
	v_max_f32_e32 v84, v84, v84
	v_min_f32_e32 v76, v76, v84
	v_max_f32_e32 v77, v77, v77
	s_waitcnt lgkmcnt(2)
	v_max_f32_e32 v85, v85, v85
	v_min_f32_e32 v77, v77, v85
	v_max_f32_e32 v78, v78, v78
	s_waitcnt lgkmcnt(1)
	v_max_f32_e32 v86, v86, v86
	v_min_f32_e32 v78, v78, v86
	v_max_f32_e32 v79, v79, v79
	s_waitcnt lgkmcnt(0)
	v_max_f32_e32 v87, v87, v87
	v_min_f32_e32 v79, v79, v87
	s_and_saveexec_b64 s[98:99], s[54:55]
	s_cbranch_execz .Lfc_skip
; __device__ __forceinline__ void fox_cumsum(const Params& P, LAS unsigned char* lds, int layer, int tid, int lane, int wave) {
;     ...
;             for (int h = 0; h < 8; ++h) { const float c = wave_scan_incl(hv[h], lane); CL[(krow0 + lane) * 8 + h] = c; const float cm = wave_min(c);
;                 if (lane == 63) { BT[(krow0 >> 6) * 8 + h] = c; CM[(krow0 >> 6) * 8 + h] = cm; } }
	s_lshl_b64 s[66:67], s[60:61], 2
	s_add_u32 s62, s5, s66
	s_addc_u32 s63, s6, s67
	s_add_u32 s66, s7, s66
	s_addc_u32 s67, s20, s67
	global_store_dword v1, v16, s[62:63]
	global_store_dword v1, v72, s[66:67]
	global_store_dword v1, v17, s[62:63] offset:4
	global_store_dword v1, v73, s[66:67] offset:4
	global_store_dword v1, v18, s[62:63] offset:8
	global_store_dword v1, v74, s[66:67] offset:8
	global_store_dword v1, v19, s[62:63] offset:12
	global_store_dword v1, v75, s[66:67] offset:12
	global_store_dword v1, v20, s[62:63] offset:16
	global_store_dword v1, v76, s[66:67] offset:16
	global_store_dword v1, v21, s[62:63] offset:20
	global_store_dword v1, v77, s[66:67] offset:20
	global_store_dword v1, v22, s[62:63] offset:24
	global_store_dword v1, v78, s[66:67] offset:24
	global_store_dword v1, v23, s[62:63] offset:28
	global_store_dword v1, v79, s[66:67] offset:28
